# late-weight conversion moved to the START of P1 for the 96 six-unit WGs (6 groups each, static), rest stays in queue; P0 wf loads batched
# speedup vs baseline: 1.0105x; 1.0015x over previous
; #define LAS __attribute__((address_space(3)))
; __global__ void __launch_bounds__(NTHREADS, 2) skel_fwd(Args args) {
;     ...
;     F.lds = (LAS unsigned char*)lds;
;     F.MISC = (volatile LAS unsigned*)(F.lds + MISC_OFF);
;     F.tid = threadIdx.x; F.lane = F.tid & 63; F.wave = __builtin_amdgcn_readfirstlane(F.tid >> 6);
;     F.G = gridDim.x; { const int bx = blockIdx.x; F.vcu = (F.G % 8 == 0) ? (bx % 8) * (F.G / 8) + bx / 8 : bx; }
;     unsigned char* ws = args.ws;
;     F.ctl = (gu32*)(ws + WS_CTL);
;     F.x = args.in[0]; F.mem = args.in[1]; F.g_mix = args.in[2]; F.g_memn = args.in[3]; F.w_in = args.in[4]; F.b_forget = args.in[5]; F.g_fq = args.in[6]; F.g_fk = args.in[7];
;     F.g_mq = args.in[8]; F.g_mk = args.in[9]; F.w_mkv = args.in[10]; F.w_bsb = args.in[11]; F.w_bfx = args.in[12]; F.w_bmm = args.in[13]; F.w_out = args.in[14]; F.g_mlp = args.in[15];
;     F.w_up = args.in[16]; F.w_dn = args.in[17]; F.out = args.out;
;     F.logf = (float*)(ws + WS_LOGF); F.FC = (float*)(ws + WS_FC); F.ssq = (float*)(ws + WS_SSQ); F.MKf = (float*)(ws + WS_MKF);
;     F.Win_t = (bf16*)(ws + WS_WIN); F.Wmkv_t = (bf16*)(ws + WS_WMKV); F.Wbr_t = (bf16*)(ws + WS_WBR); F.Wout_t = (bf16*)(ws + WS_WOUT); F.Wup_t = (bf16*)(ws + WS_WUP); F.Wdn_t = (bf16*)(ws + WS_WDN);
;     F.MHb = (bf16*)(ws + WS_MH); F.MV = (bf16*)(ws + WS_MV); F.XN = (bf16*)(ws + WS_XN);
;     F.SBQ = (bf16*)(ws + WS_SBQ); F.SBK = (bf16*)(ws + WS_SBK); F.SBV = (bf16*)(ws + WS_SBV); F.FXQ = (bf16*)(ws + WS_FXQ); F.FXK = (bf16*)(ws + WS_FXK); F.FXV = (bf16*)(ws + WS_FXV); F.MQ = (bf16*)(ws + WS_MQ);
;     F.G0 = (bf16*)args.out; F.G1 = (bf16*)args.out + (size_t)M * D; F.G2 = (bf16*)(ws + WS_G2); F.MRG = (bf16*)(ws + WS_MRG); F.U = (bf16*)(ws + WS_U);
;     for (int u = F.tid; u < (LDS_BYTES - LDSCTL_OFF) / 4; u += NTHREADS) ((LAS unsigned*)(F.lds + LDSCTL_OFF))[u] = 0u;
;     __syncthreads();
;     XcdBarrier bar; bar.bar = (unsigned*)(F.ctl + CW_BAR); bar.x = 0; bar.st = nullptr;
;     if (N_LAUNCHES == 1) bar = xcd_barrier_post((unsigned*)(F.ctl + CW_BAR), F.MISC + 8);
.LBB0_2:
	v_lshl_add_u32 v1, v0, 2, 0
	v_mov_b32_e32 v2, 0
	v_add_u32_e32 v1, 0x24000, v1
	ds_write2st64_b32 v1, v2, v2 offset1:8
	ds_write2st64_b32 v1, v2, v2 offset0:16 offset1:24
	v_or_b32_e32 v1, 0x800, v0
	s_mov_b64 s[2:3], -1
	s_and_saveexec_b64 s[4:5], s[2:3]
	v_lshl_add_u32 v3, v1, 2, 0
	v_add_u32_e32 v3, 0x24000, v3
	ds_write_b32 v3, v2
	s_or_b64 exec, exec, s[4:5]
	s_and_saveexec_b64 s[4:5], s[2:3]
	s_add_i32 s2, 0, 0x24000
	v_lshl_add_u32 v1, v1, 2, s2
	v_mov_b32_e32 v2, 0
	ds_write_b32 v1, v2 offset:2048
	s_or_b64 exec, exec, s[4:5]
	v_or_b32_e32 v1, 0xc00, v0
	v_cmp_gt_u32_e64 s[2:3], 7, 6
	v_cmp_gt_u32_e64 s[6:7], 7, 5
	s_and_saveexec_b64 s[4:5], s[6:7]
	v_lshl_add_u32 v2, v1, 2, 0
	v_add_u32_e32 v2, 0x24000, v2
	v_mov_b32_e32 v3, 0
	ds_write_b32 v2, v3
	s_or_b64 exec, exec, s[4:5]
	s_load_dwordx2 s[18:19], s[0:1], 0xa0
	s_load_dwordx8 s[56:63], s[0:1], 0x80
	s_and_saveexec_b64 s[4:5], s[2:3]
	s_add_i32 s2, 0, 0x24000
	v_lshl_add_u32 v1, v1, 2, s2
	v_mov_b32_e32 v2, 0
	ds_write_b32 v1, v2 offset:2048
	s_or_b64 exec, exec, s[4:5]
	s_load_dwordx16 s[36:51], s[0:1], 0x0
	s_waitcnt lgkmcnt(0)
	s_barrier
	s_mov_b32 s98, 1
	s_mov_b32 s99, 0
	v_cmp_eq_u32_e64 s[2:3], 0, v0
	v_writelane_b32 v247, s36, 2
	s_nop 1
	v_writelane_b32 v247, s37, 3
	v_writelane_b32 v247, s38, 4
	v_writelane_b32 v247, s39, 5
	v_writelane_b32 v247, s40, 6
	v_writelane_b32 v247, s41, 7
	v_writelane_b32 v247, s42, 8
	v_writelane_b32 v247, s43, 9
	v_writelane_b32 v247, s44, 10
	v_writelane_b32 v247, s45, 11
	v_writelane_b32 v247, s46, 12
	v_writelane_b32 v247, s47, 13
	v_writelane_b32 v247, s48, 14
	v_writelane_b32 v247, s49, 15
	v_writelane_b32 v247, s50, 16
	v_writelane_b32 v247, s51, 17
	s_load_dwordx16 s[36:51], s[0:1], 0x40
	s_add_u32 s0, s62, 0x4000
	s_addc_u32 s1, s63, 0
	s_waitcnt lgkmcnt(0)
	v_writelane_b32 v247, s36, 18
	s_nop 1
	v_writelane_b32 v247, s37, 19
	v_writelane_b32 v247, s38, 20
	v_writelane_b32 v247, s39, 21
	v_writelane_b32 v247, s40, 22
	v_writelane_b32 v247, s41, 23
	v_writelane_b32 v247, s42, 24
	v_writelane_b32 v247, s43, 25
	v_writelane_b32 v247, s44, 26
	v_writelane_b32 v247, s45, 27
	v_writelane_b32 v247, s46, 28
	v_writelane_b32 v247, s47, 29
	v_writelane_b32 v247, s48, 30
	v_writelane_b32 v247, s49, 31
	v_writelane_b32 v247, s50, 32
	v_writelane_b32 v247, s51, 33
	v_writelane_b32 v247, s0, 34
	s_nop 1
	v_writelane_b32 v247, s1, 35
	s_getreg_b32 s0, hwreg(HW_REG_XCC_ID, 0, 4)
	s_and_b32 s0, s0, 15
	v_writelane_b32 v247, s0, 36
	s_mov_b64 s[0:1], exec
	v_writelane_b32 v247, s2, 37
	s_nop 1
	v_writelane_b32 v247, s3, 38
	s_and_b64 s[2:3], s[0:1], s[2:3]
	s_mov_b64 exec, s[2:3]
	s_cbranch_execz .LBB0_13
	s_mov_b64 s[2:3], exec
	v_mbcnt_lo_u32_b32 v1, s2, 0
	v_mbcnt_hi_u32_b32 v1, s3, v1
	v_cmp_eq_u32_e32 vcc, 0, v1
	s_and_b64 s[4:5], exec, vcc
	s_mov_b64 exec, s[4:5]
	s_cbranch_execz .LBB0_13
	v_readlane_b32 s4, v247, 36
	s_bcnt1_i32_b64 s2, s[2:3]
	s_lshl_b32 s4, s4, 8
	v_mov_b32_e32 v2, s2
	v_readlane_b32 s2, v247, 34
	v_mov_b32_e32 v1, s4
	v_readlane_b32 s3, v247, 35
	s_nop 4
	global_atomic_add v1, v2, s[2:3] offset:1024

; #define LAS __attribute__((address_space(3)))
; #define VM_WAIT() asm volatile("s_waitcnt vmcnt(0)" ::: "memory")
; __global__ void __launch_bounds__(NTHREADS, 2) skel_fwd(Args args) {
;     ...
;         { pg8::EpiProj E{F.SBQ, F.G0, F.G2, F.MKf, F.MV};
;           pg8::SchedP1 S{F.G, (int)blockIdx.x, (const char*)F.XN, (const char*)F.Win_t};
;           pg8::gemm_phase<pg8::EpiProj, pg8::SchedP1, false, true, 1, DE_P1>(F.lds, D, S, E);
;           if (F.G == 256) { unsigned* qctr = (unsigned*)(F.ctl + CW_LWQ); volatile LAS unsigned* slot = F.MISC + 24;
;               VM_WAIT(); __syncthreads();
;               unsigned nx = 0; if (F.tid == 0) nx = __hip_atomic_fetch_add(qctr, 1u, __ATOMIC_RELAXED, __HIP_MEMORY_SCOPE_AGENT);
;               for (;;) {
;                   if (F.tid == 0) *slot = nx;
;                   __syncthreads();
;                   const unsigned idx = *slot;
;                   if (idx * NWAVES >= (unsigned)LATE_ITEMS) break;
;                   if (F.tid == 0) nx = __hip_atomic_fetch_add(qctr, 1u, __ATOMIC_RELAXED, __HIP_MEMORY_SCOPE_AGENT);
;                   convert_late_weights(F, F.wave, LATE_ITEMS, (int)idx * NWAVES, (int)idx * NWAVES + NWAVES);
;                   __syncthreads(); } } }
.LBB0_158:
	s_cmp_eq_u32 s98, 0
	s_cbranch_scc1 .Llwf_skip
	s_mov_b32 s98, 0
	s_cmpk_lg_i32 s80, 0x100
	s_cbranch_scc1 .Llwf_skip
	s_cmpk_lt_i32 s90, 0xa0
	s_cbranch_scc1 .Llwf_skip
	s_mov_b32 s99, 1
	s_sub_i32 s100, s90, 0xa0
	s_mul_i32 s100, s100, 6
	s_add_i32 s101, s100, 6
	s_branch .LBB0_252

; #define LAS __attribute__((address_space(3)))
; #define VM_WAIT() asm volatile("s_waitcnt vmcnt(0)" ::: "memory")
;     LAS float* scr = (LAS float*)(F.lds + F.wave * 8448);
;     constexpr int I_BR = 8 * 32, I_OUT = 16 * 32, I_UP = 16 * 128;
;     for (int it = lo + w; it < NITEMS; it += nw) {
;         int r = it;
;         if (r < I_BR) { const int kb = r / 32, gi = r % 32; tr_item(F.w_bsb, D, DH, F.Wbr_t, 32 * gi, 32 * gi, 64 * kb, scr, F.lane); continue; } r -= I_BR;
;         if (r < I_BR) { const int kb = r / 32, gi = r % 32; tr_item(F.w_bfx, D, DH, F.Wbr_t + (size_t)D * DH, 32 * gi, 32 * gi, 64 * kb, scr, F.lane); continue; } r -= I_BR;
;         if (r < I_BR) { const int kb = r / 32, gi = r % 32; tr_item(F.w_bmm, D, DH, F.Wbr_t + (size_t)2 * D * DH, 32 * gi, 32 * gi, 64 * kb, scr, F.lane); continue; } r -= I_BR;
;         if (r < I_OUT) { const int kb = r / 32, gi = r % 32; tr_item(F.w_out, D, D, F.Wout_t, 32 * gi, 32 * gi, 64 * kb, scr, F.lane); continue; } r -= I_OUT;
;         if (r < I_UP) { const int kb = r / 128, gi = r % 128; tr_item(F.w_up, FF, D, F.Wup_t, 32 * gi, 32 * gi, 64 * kb, scr, F.lane, F.g_mlp); continue; } r -= I_UP;
;         { const int kb = r / 32, gi = r % 32; tr_item(F.w_dn, D, FF, F.Wdn_t, 32 * gi, 32 * gi, 64 * kb, scr, F.lane); }
; __global__ void __launch_bounds__(NTHREADS, 2) skel_fwd(Args args) {
;     ...
;           if (F.G == 256) { unsigned* qctr = (unsigned*)(F.ctl + CW_LWQ); volatile LAS unsigned* slot = F.MISC + 24;
;               VM_WAIT(); __syncthreads();
;               unsigned nx = 0; if (F.tid == 0) nx = __hip_atomic_fetch_add(qctr, 1u, __ATOMIC_RELAXED, __HIP_MEMORY_SCOPE_AGENT);
;               for (;;) {
;                   if (F.tid == 0) *slot = nx;
;                   __syncthreads();
;                   const unsigned idx = *slot;
;                   if (idx * NWAVES >= (unsigned)LATE_ITEMS) break;
;                   if (F.tid == 0) nx = __hip_atomic_fetch_add(qctr, 1u, __ATOMIC_RELAXED, __HIP_MEMORY_SCOPE_AGENT);
;                   convert_late_weights(F, F.wave, LATE_ITEMS, (int)idx * NWAVES, (int)idx * NWAVES + NWAVES);
.LBB0_252:
	s_waitcnt vmcnt(0)
	s_add_u32 s0, s62, 0x2000
	s_addc_u32 s1, s63, 0
	v_mov_b32_e32 v1, 0
	s_waitcnt vmcnt(0) lgkmcnt(0)
	s_barrier
	s_mov_b64 s[2:3], exec
	v_readlane_b32 s4, v247, 37
	v_readlane_b32 s5, v247, 38
	s_and_b64 s[4:5], s[2:3], s[4:5]
	s_mov_b64 exec, s[4:5]
	s_cbranch_execz .LBB0_256
	s_mov_b64 s[6:7], exec
	v_mbcnt_lo_u32_b32 v1, s6, 0
	v_mbcnt_hi_u32_b32 v1, s7, v1
	v_cmp_eq_u32_e32 vcc, 0, v1
	s_and_saveexec_b64 s[4:5], vcc
	s_cbranch_execz .LBB0_255
	s_bcnt1_i32_b64 s6, s[6:7]
	v_mov_b32_e32 v2, 0
	s_cmp_eq_u32 s99, 1
	s_cselect_b32 s6, 6, s6
	v_mov_b32_e32 v3, s6
	global_atomic_add v2, v2, v3, s[0:1] sc0
.LBB0_255:
	s_or_b64 exec, exec, s[4:5]
	s_waitcnt vmcnt(0)
	v_readfirstlane_b32 s4, v2
	s_nop 1
	v_add_u32_e32 v1, s4, v1
	s_cmp_eq_u32 s99, 1
	s_cbranch_scc0 .Llwf_first_idx
	v_mov_b32_e32 v1, s100
.Llwf_first_idx:
.LBB0_256:
	s_or_b64 exec, exec, s[2:3]
	v_lshrrev_b32_e32 v48, 5, v178
	s_movk_i32 s5, 0x84
	v_or_b32_e32 v10, 2, v48
	v_mov_b32_e32 v11, 0x108
	s_mul_i32 s2, s81, 0x2100
	v_and_b32_e32 v2, 31, v0
	v_lshlrev_b32_e32 v6, 3, v0
	v_mad_u32_u24 v30, v10, s5, v11
	v_mov_b32_e32 v11, 0x318
	s_add_i32 s4, s2, 0
	v_lshlrev_b32_e32 v2, 2, v2
	v_lshrrev_b32_e32 v50, 3, v178
	v_and_b32_e32 v6, 56, v6
	v_mad_u32_u24 v31, v10, s5, v11
	v_mov_b32_e32 v11, 0x528
	v_add_u32_e32 v28, s4, v2
	v_mul_u32_u24_e32 v8, 0x84, v6
	v_lshlrev_b32_e32 v9, 2, v50
	v_mad_u32_u24 v32, v10, s5, v11
	v_mov_b32_e32 v11, 0x738
	v_mov_b32_e32 v3, 0
	v_mad_u32_u24 v49, v48, s5, v28
	v_add3_u32 v51, s4, v8, v9
	v_mad_u32_u24 v33, v10, s5, v11
	v_readlane_b32 s4, v247, 41
	v_lshlrev_b32_e32 v26, 1, v6
	v_mov_b32_e32 v27, v3
	v_readlane_b32 s5, v247, 42
	v_mul_u32_u24_e32 v29, 0x84, v10
	v_readlane_b32 s12, v247, 18
	v_lshl_add_u64 v[10:11], s[4:5], 0, v[26:27]
	v_readlane_b32 s4, v247, 43
	v_readlane_b32 s5, v247, 44
	v_lshl_add_u64 v[22:23], s[62:63], 0, v[26:27]
	s_cmpk_lt_u32 s88, 0x200
	v_lshl_add_u64 v[14:15], s[4:5], 0, v[26:27]
	s_mov_b64 s[4:5], 0x1400000
	v_readlane_b32 s26, v247, 32
	v_readlane_b32 s27, v247, 33
	v_lshl_add_u64 v[18:19], v[22:23], 0, s[4:5]
	s_mov_b64 s[4:5], 0x1300000
	s_cselect_b64 s[2:3], -1, 0
	v_readlane_b32 s6, v247, 45
	v_readlane_b32 s18, v247, 24
	v_readlane_b32 s19, v247, 25
	v_readlane_b32 s20, v247, 26
	v_readlane_b32 s21, v247, 27
	v_readlane_b32 s22, v247, 28
	v_readlane_b32 s23, v247, 29
	v_readlane_b32 s24, v247, 30
	v_readlane_b32 s25, v247, 31
	s_cmp_lg_u64 s[26:27], 0
	v_lshl_add_u64 v[22:23], v[22:23], 0, s[4:5]
	v_readlane_b32 s4, v247, 39
	v_lshl_add_u64 v[4:5], s[58:59], 0, v[2:3]
	v_readlane_b32 s7, v247, 46
	v_lshl_add_u64 v[8:9], s[56:57], 0, v[2:3]
	v_readlane_b32 s16, v247, 22
	v_readlane_b32 s17, v247, 23
	s_cselect_b64 s[10:11], -1, 0
	v_lshl_add_u64 v[12:13], s[24:25], 0, v[2:3]
	v_lshl_add_u64 v[16:17], s[22:23], 0, v[2:3]
	v_lshl_add_u64 v[20:21], s[20:21], 0, v[2:3]
	v_lshl_add_u64 v[24:25], s[18:19], 0, v[2:3]
	v_readlane_b32 s5, v247, 40
	s_add_i32 s18, 0, 0x241a0
	v_cndmask_b32_e64 v2, 0, 1, s[2:3]
	s_mov_b32 s9, 0
	v_lshl_add_u64 v[6:7], s[6:7], 0, v[26:27]
	v_or_b32_e32 v52, 8, v50
	v_or_b32_e32 v53, 16, v50
	v_or_b32_e32 v54, 24, v50
	v_lshl_add_u64 v[26:27], s[4:5], 0, v[26:27]
	s_lshl_b32 s16, s81, 5
	s_lshl_b32 s17, s81, 1
	v_mov_b32_e32 v55, s18
	v_cmp_ne_u32_e64 s[6:7], 1, v2
	s_movk_i32 s19, 0x7fff
	s_mov_b32 s20, 0xffff0000
	v_add_u32_e32 v56, v28, v30
	v_add_u32_e32 v57, v28, v32
	v_add_u32_e32 v58, 0x400, v49
	v_add_u32_e32 v59, 0x800, v49
	v_add_u32_e32 v60, 0xc00, v49
	v_add_u32_e32 v61, 0x1000, v49
	v_add_u32_e32 v62, 0x1400, v49
	v_add_u32_e32 v63, 0x1800, v49
	v_add_u32_e32 v64, 0x1c00, v49
	v_add_u32_e32 v65, v28, v29
	v_add_u32_e32 v66, v28, v31
	v_add_u32_e32 v67, v28, v33
	v_readlane_b32 s13, v247, 19
	v_readlane_b32 s14, v247, 20
	v_readlane_b32 s15, v247, 21
	s_branch .LBB0_259

; __global__ void __launch_bounds__(NTHREADS, 2) skel_fwd(Args args) {
;     ...
;               for (;;) {
;                   if (F.tid == 0) *slot = nx;
;                   __syncthreads();
;                   const unsigned idx = *slot;
;                   if (idx * NWAVES >= (unsigned)LATE_ITEMS) break;
;                   if (F.tid == 0) nx = __hip_atomic_fetch_add(qctr, 1u, __ATOMIC_RELAXED, __HIP_MEMORY_SCOPE_AGENT);
;                   convert_late_weights(F, F.wave, LATE_ITEMS, (int)idx * NWAVES, (int)idx * NWAVES + NWAVES);
.LBB0_259:
	s_mov_b64 s[2:3], exec
	v_readlane_b32 s4, v247, 37
	v_readlane_b32 s5, v247, 38
	s_and_b64 s[4:5], s[2:3], s[4:5]
	s_mov_b64 exec, s[4:5]
	v_mov_b32_e32 v2, s18
	ds_write_b32 v2, v1
	s_or_b64 exec, exec, s[2:3]
	s_waitcnt lgkmcnt(0)
	s_barrier
	ds_read_b32 v2, v55
	s_waitcnt lgkmcnt(0)
	v_readfirstlane_b32 s8, v2
	s_lshl_b32 s21, s8, 3
	s_cmpk_gt_u32 s21, 0x14ff
	s_cselect_b64 s[12:13], -1, 0
	s_and_b64 vcc, exec, s[12:13]
	s_cbranch_vccnz .LBB0_258
	s_cmp_eq_u32 s99, 1
	s_cbranch_scc0 .Llwf_queue_next
	s_add_i32 s4, s8, 1
	s_cmp_ge_u32 s4, s101
	s_cselect_b32 s14, 0x2a0, s4
	s_mov_b64 s[2:3], exec
	v_readlane_b32 s4, v247, 37
	v_readlane_b32 s5, v247, 38
	s_nop 3
	s_and_b64 s[4:5], s[2:3], s[4:5]
	s_mov_b64 exec, s[4:5]
	v_mov_b32_e32 v1, s14
	s_mov_b64 exec, s[2:3]
	s_branch .LBB0_266
.Llwf_queue_next:
	s_mov_b64 s[2:3], exec
	v_readlane_b32 s4, v247, 37
	v_readlane_b32 s5, v247, 38
	s_and_b64 s[4:5], s[2:3], s[4:5]
	s_mov_b64 exec, s[4:5]
	s_cbranch_execz .LBB0_266
	s_mov_b64 s[14:15], exec
	v_mbcnt_lo_u32_b32 v1, s14, 0
	v_mbcnt_hi_u32_b32 v1, s15, v1
	v_cmp_eq_u32_e32 vcc, 0, v1
	s_and_saveexec_b64 s[4:5], vcc
	s_cbranch_execz .LBB0_265
	s_bcnt1_i32_b64 s14, s[14:15]
	v_mov_b32_e32 v2, s14
	global_atomic_add v2, v3, v2, s[0:1] sc0

; #define LAS __attribute__((address_space(3)))
; #define VM_WAIT() asm volatile("s_waitcnt vmcnt(0)" ::: "memory")
; __global__ void __launch_bounds__(NTHREADS, 2) skel_fwd(Args args) {
;     ...
;           if (F.G == 256) { unsigned* qctr = (unsigned*)(F.ctl + CW_LWQ); volatile LAS unsigned* slot = F.MISC + 24;
;               VM_WAIT(); __syncthreads();
;               unsigned nx = 0; if (F.tid == 0) nx = __hip_atomic_fetch_add(qctr, 1u, __ATOMIC_RELAXED, __HIP_MEMORY_SCOPE_AGENT);
;               for (;;) {
;                   if (F.tid == 0) *slot = nx;
;                   __syncthreads();
;                   const unsigned idx = *slot;
;                   if (idx * NWAVES >= (unsigned)LATE_ITEMS) break;
;                   if (F.tid == 0) nx = __hip_atomic_fetch_add(qctr, 1u, __ATOMIC_RELAXED, __HIP_MEMORY_SCOPE_AGENT);
;                   convert_late_weights(F, F.wave, LATE_ITEMS, (int)idx * NWAVES, (int)idx * NWAVES + NWAVES);
;                   __syncthreads(); } } }
.LBB0_321:
	s_cmp_eq_u32 s99, 1
	s_cbranch_scc0 .Llwf_exit_normal
	s_mov_b32 s99, 0
	s_add_u32 s22, s62, 0x300000
	s_addc_u32 s23, s63, 0
	v_readlane_b32 s18, v247, 47
	v_readlane_b32 s19, v247, 48
	s_waitcnt vmcnt(0) lgkmcnt(0)
	s_branch .Llwf_skip

; __global__ void __launch_bounds__(NTHREADS, 2) skel_fwd(Args args) {
	.amdhsa_kernel _Z8skel_fwd4Args
		.amdhsa_group_segment_fixed_size 0
		.amdhsa_private_segment_fixed_size 0
		.amdhsa_kernarg_size 432
		.amdhsa_user_sgpr_count 2
		.amdhsa_user_sgpr_dispatch_ptr 0
		.amdhsa_user_sgpr_queue_ptr 0
		.amdhsa_user_sgpr_kernarg_segment_ptr 1
		.amdhsa_user_sgpr_dispatch_id 0
		.amdhsa_user_sgpr_kernarg_preload_length 0
		.amdhsa_user_sgpr_kernarg_preload_offset 0
		.amdhsa_user_sgpr_private_segment_size 0
		.amdhsa_uses_dynamic_stack 0
		.amdhsa_enable_private_segment 0
		.amdhsa_system_sgpr_workgroup_id_x 1
		.amdhsa_system_sgpr_workgroup_id_y 0
		.amdhsa_system_sgpr_workgroup_id_z 0
		.amdhsa_system_sgpr_workgroup_info 0
		.amdhsa_system_vgpr_workitem_id 0
		.amdhsa_next_free_vgpr 248
		.amdhsa_next_free_sgpr 102
		.amdhsa_accum_offset 248
		.amdhsa_reserve_vcc 1
		.amdhsa_float_round_mode_32 0
		.amdhsa_float_round_mode_16_64 0
		.amdhsa_float_denorm_mode_32 3
		.amdhsa_float_denorm_mode_16_64 3
		.amdhsa_dx10_clamp 1
		.amdhsa_ieee_mode 1
		.amdhsa_fp16_overflow 0
		.amdhsa_tg_split 0
		.amdhsa_exception_fp_ieee_invalid_op 0
		.amdhsa_exception_fp_denorm_src 0
		.amdhsa_exception_fp_ieee_div_zero 0
		.amdhsa_exception_fp_ieee_overflow 0
		.amdhsa_exception_fp_ieee_underflow 0
		.amdhsa_exception_fp_ieee_inexact 0
		.amdhsa_exception_int_div_zero 0
	.end_amdhsa_kernel

; __global__ void __launch_bounds__(NTHREADS, 2) skel_fwd(Args args) {
amdhsa.kernels:
  - .agpr_count:     0
    .args:
      - .offset:         0
        .size:           176
        .value_kind:     by_value
      - .offset:         176
        .size:           4
        .value_kind:     hidden_block_count_x
      - .offset:         180
        .size:           4
        .value_kind:     hidden_block_count_y
      - .offset:         184
        .size:           4
        .value_kind:     hidden_block_count_z
      - .offset:         188
        .size:           2
        .value_kind:     hidden_group_size_x
      - .offset:         190
        .size:           2
        .value_kind:     hidden_group_size_y
      - .offset:         192
        .size:           2
        .value_kind:     hidden_group_size_z
      - .offset:         194
        .size:           2
        .value_kind:     hidden_remainder_x
      - .offset:         196
        .size:           2
        .value_kind:     hidden_remainder_y
      - .offset:         198
        .size:           2
        .value_kind:     hidden_remainder_z
      - .offset:         216
        .size:           8
        .value_kind:     hidden_global_offset_x
      - .offset:         224
        .size:           8
        .value_kind:     hidden_global_offset_y
      - .offset:         232
        .size:           8
        .value_kind:     hidden_global_offset_z
      - .offset:         240
        .size:           2
        .value_kind:     hidden_grid_dims
      - .offset:         296
        .size:           4
        .value_kind:     hidden_dynamic_lds_size
    .group_segment_fixed_size: 0
    .kernarg_segment_align: 8
    .kernarg_segment_size: 432
    .language:       OpenCL C
    .language_version:
      - 2
      - 0
    .max_flat_workgroup_size: 512
    .name:           _Z8skel_fwd4Args
    .private_segment_fixed_size: 0
    .sgpr_count:     108
    .sgpr_spill_count: 113
    .symbol:         _Z8skel_fwd4Args.kd
    .uniform_work_group_size: 1
    .uses_dynamic_stack: false
    .vgpr_count:     248
    .vgpr_spill_count: 0
    .wavefront_size: 64
